# FFN-up epilogue: two input register banks (no carry moves), wave-uniform store-address switch (scalar), dead address arithmetic of the hoisted weight loads removed
# speedup vs baseline: 1.0308x; 1.0019x over previous
.LBB0_683:
	s_or_b64 exec, exec, s[4:5]
	v_pk_mul_f32 v[2:3], v[2:3], v[66:67] op_sel_hi:[1,0]
	ds_write2_b32 v155, v2, v3 offset0:32 offset1:33
	v_pk_mul_f32 v[2:3], v[4:5], v[66:67] op_sel_hi:[1,0]
	ds_write2_b32 v155, v2, v3 offset0:34 offset1:35
	v_pk_mul_f32 v[2:3], v[6:7], v[66:67] op_sel_hi:[1,0]
	ds_write2_b32 v155, v2, v3 offset0:40 offset1:41
	v_pk_mul_f32 v[2:3], v[8:9], v[66:67] op_sel_hi:[1,0]
	ds_write2_b32 v155, v2, v3 offset0:42 offset1:43
	v_pk_mul_f32 v[2:3], v[10:11], v[66:67] op_sel_hi:[1,0]
	ds_write2_b32 v155, v2, v3 offset0:48 offset1:49
	v_pk_mul_f32 v[2:3], v[12:13], v[66:67] op_sel_hi:[1,0]
	ds_write2_b32 v155, v2, v3 offset0:50 offset1:51
	v_pk_mul_f32 v[2:3], v[14:15], v[66:67] op_sel_hi:[1,0]
	ds_write2_b32 v155, v2, v3 offset0:56 offset1:57
	v_pk_mul_f32 v[2:3], v[16:17], v[66:67] op_sel_hi:[1,0]
	ds_write2_b32 v155, v2, v3 offset0:58 offset1:59
	v_pk_mul_f32 v[18:19], v[18:19], v[66:67] op_sel_hi:[1,0]
	ds_write2_b32 v155, v18, v19 offset1:1
	v_pk_mul_f32 v[18:19], v[20:21], v[66:67] op_sel_hi:[1,0]
	ds_write2_b32 v155, v18, v19 offset0:2 offset1:3
	v_pk_mul_f32 v[18:19], v[22:23], v[66:67] op_sel_hi:[1,0]
	ds_write2_b32 v155, v18, v19 offset0:8 offset1:9
	v_pk_mul_f32 v[18:19], v[24:25], v[66:67] op_sel_hi:[1,0]
	ds_write2_b32 v155, v18, v19 offset0:10 offset1:11
	v_pk_mul_f32 v[18:19], v[26:27], v[66:67] op_sel_hi:[1,0]
	ds_write2_b32 v155, v18, v19 offset0:16 offset1:17
	v_pk_mul_f32 v[18:19], v[28:29], v[66:67] op_sel_hi:[1,0]
	ds_write2_b32 v155, v18, v19 offset0:18 offset1:19
	v_pk_mul_f32 v[18:19], v[30:31], v[66:67] op_sel_hi:[1,0]
	ds_write2_b32 v155, v18, v19 offset0:24 offset1:25
	v_pk_mul_f32 v[18:19], v[32:33], v[66:67] op_sel_hi:[1,0]
	ds_write2_b32 v155, v18, v19 offset0:26 offset1:27
	s_waitcnt lgkmcnt(0)
	s_barrier
	s_waitcnt vmcnt(0)
	v_mov_b32_e32 v3, v188
	v_mov_b32_e32 v5, v189
	v_mov_b32_e32 v7, v190
	v_mov_b32_e32 v9, v191
	v_mov_b32_e32 v2, v192
	v_mov_b32_e32 v4, v193
	v_mov_b32_e32 v6, v194
	s_mul_i32 s4, s51, 0x7e
	v_mov_b32_e32 v8, v195
	ds_read_b32 v15, v159
	ds_read_b32 v10, v160
	ds_read_b32 v14, v161
	ds_read_b32 v11, v162
	s_add_i32 s4, s21, s4
	s_mulk_i32 s52, 0x7c
	s_sub_i32 s10, s4, s52
	s_mov_b64 s[4:5], 0
	v_mov_b32_e32 v17, v158
	v_mov_b32_e32 v18, v156
	s_waitcnt vmcnt(0)
	s_add_i32 s63, s10, -2
	s_sub_i32 s64, s22, s50
	v_min_i32_e32 v40, s64, v157
	v_add_u32_e32 v40, s63, v40
	v_lshlrev_b32_e32 v41, 1, v114
	v_add_u32_e32 v32, s63, v18
	v_ashrrev_i32_e32 v220, 7, v32
	v_and_b32_e32 v24, 0x7f, v32
	v_mad_u32_u24 v220, v220, 44, s14
	v_subrev_u32_e32 v33, 64, v24
	v_lshlrev_b32_e32 v24, 7, v24
	v_sub_u32_e32 v34, v40, v32
	v_readfirstlane_b32 s64, v33
	v_lshl_or_b32 v24, v220, 14, v24
	v_add_u32_e32 v39, v24, v41
	v_add_u32_e32 v35, 0xac000, v39
	v_add_u32_e32 v36, 1032, v17
	v_add_u32_e32 v37, 2064, v17
	v_add_u32_e32 v38, 3096, v17
	ds_read2_b32 v[188:189], v17 offset0:0 offset1:64
	ds_read2_b32 v[190:191], v17 offset0:129 offset1:193
	ds_read2_b32 v[192:193], v36 offset0:0 offset1:64
	ds_read2_b32 v[194:195], v36 offset0:129 offset1:193
	ds_read2_b32 v[196:197], v37 offset0:0 offset1:64
	ds_read2_b32 v[198:199], v37 offset0:129 offset1:193
	ds_read2_b32 v[200:201], v38 offset0:0 offset1:64
	ds_read2_b32 v[202:203], v38 offset0:129 offset1:193
	s_cmp_ge_i32 s64, 64
	s_cselect_b32 s62, 0xac000, 0
	s_cselect_b32 s61, 0, 1
	s_cbranch_scc1 .Lcv5_uni0
	s_cmp_lt_i32 s64, 57
	s_cbranch_scc1 .Lcv5_uni0
	s_mov_b32 s61, 2
	v_cmp_le_i32_e64 s[6:7], 64, v33
	v_cmp_le_i32_e64 s[8:9], 63, v33
	v_cmp_le_i32_e64 vcc, 62, v33
	v_cndmask_b32_e64 v24, v39, v35, s[6:7]
	v_cmp_le_i32_e64 s[6:7], 61, v33
	v_cndmask_b32_e64 v25, v39, v35, s[8:9]
	v_cmp_le_i32_e64 s[8:9], 60, v33
	v_cndmask_b32_e64 v26, v39, v35, vcc
	v_cmp_le_i32_e64 vcc, 59, v33
	v_cndmask_b32_e64 v27, v39, v35, s[6:7]
	v_cmp_le_i32_e64 s[6:7], 58, v33
	v_cndmask_b32_e64 v28, v39, v35, s[8:9]
	v_cmp_le_i32_e64 s[8:9], 57, v33
	v_cndmask_b32_e64 v29, v39, v35, vcc
	v_cndmask_b32_e64 v30, v39, v35, s[6:7]
	s_nop 0
	v_cndmask_b32_e64 v31, v39, v35, s[8:9]
	s_branch .Lcv5_adr0
.Lcv5_uni0:
	v_add_u32_e32 v24, s62, v39
.Lcv5_adr0:
	s_waitcnt lgkmcnt(0)
	v_fma_f32 v204, v3, v15, v9
	v_fma_f32 v212, v2, v14, v8
	v_fma_f32 v205, v3, v10, v9
	v_fma_f32 v213, v2, v11, v8
	v_fma_f32 v206, v3, v188, v9
	v_fma_f32 v214, v2, v189, v8
	v_fma_f32 v207, v3, v190, v9
	v_fma_f32 v215, v2, v191, v8
	v_fma_f32 v208, v3, v192, v9
	v_fma_f32 v216, v2, v193, v8
	v_fma_f32 v209, v3, v194, v9
	v_fma_f32 v217, v2, v195, v8
	v_fma_f32 v210, v3, v196, v9
	v_fma_f32 v218, v2, v197, v8
	v_fma_f32 v211, v3, v198, v9
	v_fma_f32 v219, v2, v199, v8
	v_fma_f32 v204, v5, v10, v204
	v_fma_f32 v212, v4, v11, v212
	v_fma_f32 v205, v5, v188, v205
	v_fma_f32 v213, v4, v189, v213
	v_fma_f32 v206, v5, v190, v206
	v_fma_f32 v214, v4, v191, v214
	v_fma_f32 v207, v5, v192, v207
	v_fma_f32 v215, v4, v193, v215
	v_fma_f32 v208, v5, v194, v208
	v_fma_f32 v216, v4, v195, v216
	v_fma_f32 v209, v5, v196, v209
	v_fma_f32 v217, v4, v197, v217
	v_fma_f32 v210, v5, v198, v210
	v_fma_f32 v218, v4, v199, v218
	v_fma_f32 v211, v5, v200, v211
	v_fma_f32 v219, v4, v201, v219
	v_fma_f32 v204, v7, v188, v204
	v_fma_f32 v212, v6, v189, v212
	v_fma_f32 v205, v7, v190, v205
	v_fma_f32 v213, v6, v191, v213
	v_fma_f32 v206, v7, v192, v206
	v_fma_f32 v214, v6, v193, v214
	v_fma_f32 v207, v7, v194, v207
	v_fma_f32 v215, v6, v195, v215
	v_fma_f32 v208, v7, v196, v208
	v_fma_f32 v216, v6, v197, v216
	v_fma_f32 v209, v7, v198, v209
	v_fma_f32 v217, v6, v199, v217
	v_fma_f32 v210, v7, v200, v210
	v_fma_f32 v218, v6, v201, v218
	v_fma_f32 v211, v7, v202, v211
	v_fma_f32 v219, v6, v203, v219
	v_mul_f32_e32 v220, 0xbfb8aa3b, v204
	v_mul_f32_e32 v221, 0xbfb8aa3b, v205
	v_mul_f32_e32 v222, 0xbfb8aa3b, v206
	v_mul_f32_e32 v223, 0xbfb8aa3b, v207
	v_mul_f32_e32 v224, 0xbfb8aa3b, v208
	v_mul_f32_e32 v225, 0xbfb8aa3b, v209
	v_mul_f32_e32 v226, 0xbfb8aa3b, v210
	v_mul_f32_e32 v227, 0xbfb8aa3b, v211
	v_exp_f32_e32 v220, v220
	v_exp_f32_e32 v221, v221
	v_exp_f32_e32 v222, v222
	v_exp_f32_e32 v223, v223
	v_exp_f32_e32 v224, v224
	v_exp_f32_e32 v225, v225
	v_exp_f32_e32 v226, v226
	v_exp_f32_e32 v227, v227
	v_add_f32_e32 v220, 1.0, v220
	v_add_f32_e32 v221, 1.0, v221
	v_add_f32_e32 v222, 1.0, v222
	v_add_f32_e32 v223, 1.0, v223
	v_add_f32_e32 v224, 1.0, v224
	v_add_f32_e32 v225, 1.0, v225
	v_add_f32_e32 v226, 1.0, v226
	v_add_f32_e32 v227, 1.0, v227
	v_rcp_f32_e32 v220, v220
	v_rcp_f32_e32 v221, v221
	v_rcp_f32_e32 v222, v222
	v_rcp_f32_e32 v223, v223
	v_rcp_f32_e32 v224, v224
	v_rcp_f32_e32 v225, v225
	v_rcp_f32_e32 v226, v226
	v_rcp_f32_e32 v227, v227
	v_mul_f32_e32 v204, v204, v220
	v_mul_f32_e32 v205, v205, v221
	v_mul_f32_e32 v206, v206, v222
	v_mul_f32_e32 v207, v207, v223
	v_mul_f32_e32 v208, v208, v224
	v_mul_f32_e32 v209, v209, v225
	v_mul_f32_e32 v210, v210, v226
	v_mul_f32_e32 v211, v211, v227
	v_mul_f32_e32 v212, v212, v204
	v_mul_f32_e32 v213, v213, v205
	v_mul_f32_e32 v214, v214, v206
	v_mul_f32_e32 v215, v215, v207
	v_mul_f32_e32 v216, v216, v208
	v_mul_f32_e32 v217, v217, v209
	v_mul_f32_e32 v218, v218, v210
	v_mul_f32_e32 v219, v219, v211
	v_cvt_pk_bf16_f32 v212, v212, v213
	v_cvt_pk_bf16_f32 v214, v214, v215
	v_cvt_pk_bf16_f32 v216, v216, v217
	v_cvt_pk_bf16_f32 v218, v218, v219
	s_cmp_eq_u32 s61, 2
	s_cbranch_scc1 .Lcv5_mst0
	v_cmp_gt_i32_e32 vcc, 8, v34
	s_cmp_lg_u64 vcc, 0
	s_cbranch_scc1 .Lcv5_slowu0
	global_store_short v24, v212, s[42:43]
	global_store_short_d16_hi v24, v212, s[42:43] offset:128
	global_store_short v24, v214, s[42:43] offset:256
	global_store_short_d16_hi v24, v214, s[42:43] offset:384
	global_store_short v24, v216, s[42:43] offset:512
	global_store_short_d16_hi v24, v216, s[42:43] offset:640
	global_store_short v24, v218, s[42:43] offset:768
	global_store_short_d16_hi v24, v218, s[42:43] offset:896
	s_branch .Lcv5_next0
.Lcv5_slowu0:
	v_cmp_lt_i32_e32 vcc, 0, v34
	s_and_b64 exec, exec, vcc
	global_store_short v24, v212, s[42:43]
	v_cmp_lt_i32_e32 vcc, 1, v34
	s_and_b64 exec, exec, vcc
	global_store_short_d16_hi v24, v212, s[42:43] offset:128
	v_cmp_lt_i32_e32 vcc, 2, v34
	s_and_b64 exec, exec, vcc
	global_store_short v24, v214, s[42:43] offset:256
	v_cmp_lt_i32_e32 vcc, 3, v34
	s_and_b64 exec, exec, vcc
	global_store_short_d16_hi v24, v214, s[42:43] offset:384
	v_cmp_lt_i32_e32 vcc, 4, v34
	s_and_b64 exec, exec, vcc
	global_store_short v24, v216, s[42:43] offset:512
	v_cmp_lt_i32_e32 vcc, 5, v34
	s_and_b64 exec, exec, vcc
	global_store_short_d16_hi v24, v216, s[42:43] offset:640
	v_cmp_lt_i32_e32 vcc, 6, v34
	s_and_b64 exec, exec, vcc
	global_store_short v24, v218, s[42:43] offset:768
	v_cmp_lt_i32_e32 vcc, 7, v34
	s_and_b64 exec, exec, vcc
	global_store_short_d16_hi v24, v218, s[42:43] offset:896
	s_mov_b64 exec, -1
	s_branch .Lcv5_next0
.Lcv5_mst0:
	v_cmp_gt_i32_e32 vcc, 8, v34
	s_cmp_lg_u64 vcc, 0
	s_cbranch_scc1 .Lcv5_slowm0
	global_store_short v24, v212, s[42:43]
	global_store_short_d16_hi v25, v212, s[42:43] offset:128
	global_store_short v26, v214, s[42:43] offset:256
	global_store_short_d16_hi v27, v214, s[42:43] offset:384
	global_store_short v28, v216, s[42:43] offset:512
	global_store_short_d16_hi v29, v216, s[42:43] offset:640
	global_store_short v30, v218, s[42:43] offset:768
	global_store_short_d16_hi v31, v218, s[42:43] offset:896
	s_branch .Lcv5_next0

.Lcv5_next0:
	v_add_u32_e32 v17, 0x1020, v17
	v_add_u32_e32 v36, 1032, v17
	v_add_u32_e32 v37, 2064, v17
	v_add_u32_e32 v38, 3096, v17
	ds_read2_b32 v[42:43], v17 offset0:0 offset1:64
	ds_read2_b32 v[44:45], v17 offset0:129 offset1:193
	ds_read2_b32 v[46:47], v36 offset0:0 offset1:64
	ds_read2_b32 v[48:49], v36 offset0:129 offset1:193
	ds_read2_b32 v[50:51], v37 offset0:0 offset1:64
	ds_read2_b32 v[52:53], v37 offset0:129 offset1:193
	ds_read2_b32 v[54:55], v38 offset0:0 offset1:64
	ds_read2_b32 v[56:57], v38 offset0:129 offset1:193
	s_cmp_ge_i32 s64, 56
	s_cselect_b32 s62, 0xac000, 0
	s_cselect_b32 s61, 0, 1
	s_cbranch_scc1 .Lcv5_uni1
	s_cmp_lt_i32 s64, 49
	s_cbranch_scc1 .Lcv5_uni1
	s_mov_b32 s61, 2
	v_cmp_le_i32_e64 s[6:7], 56, v33
	v_cmp_le_i32_e64 s[8:9], 55, v33
	v_cmp_le_i32_e64 vcc, 54, v33
	v_cndmask_b32_e64 v24, v39, v35, s[6:7]
	v_cmp_le_i32_e64 s[6:7], 53, v33
	v_cndmask_b32_e64 v25, v39, v35, s[8:9]
	v_cmp_le_i32_e64 s[8:9], 52, v33
	v_cndmask_b32_e64 v26, v39, v35, vcc
	v_cmp_le_i32_e64 vcc, 51, v33
	v_cndmask_b32_e64 v27, v39, v35, s[6:7]
	v_cmp_le_i32_e64 s[6:7], 50, v33
	v_cndmask_b32_e64 v28, v39, v35, s[8:9]
	v_cmp_le_i32_e64 s[8:9], 49, v33
	v_cndmask_b32_e64 v29, v39, v35, vcc
	v_cndmask_b32_e64 v30, v39, v35, s[6:7]
	s_nop 0
	v_cndmask_b32_e64 v31, v39, v35, s[8:9]
	s_branch .Lcv5_adr1

.Lcv5_adr1:
	s_waitcnt lgkmcnt(0)
	v_fma_f32 v204, v3, v200, v9
	v_fma_f32 v212, v2, v201, v8
	v_fma_f32 v205, v3, v202, v9
	v_fma_f32 v213, v2, v203, v8
	v_fma_f32 v206, v3, v42, v9
	v_fma_f32 v214, v2, v43, v8
	v_fma_f32 v207, v3, v44, v9
	v_fma_f32 v215, v2, v45, v8
	v_fma_f32 v208, v3, v46, v9
	v_fma_f32 v216, v2, v47, v8
	v_fma_f32 v209, v3, v48, v9
	v_fma_f32 v217, v2, v49, v8
	v_fma_f32 v210, v3, v50, v9
	v_fma_f32 v218, v2, v51, v8
	v_fma_f32 v211, v3, v52, v9
	v_fma_f32 v219, v2, v53, v8
	v_fma_f32 v204, v5, v202, v204
	v_fma_f32 v212, v4, v203, v212
	v_fma_f32 v205, v5, v42, v205
	v_fma_f32 v213, v4, v43, v213
	v_fma_f32 v206, v5, v44, v206
	v_fma_f32 v214, v4, v45, v214
	v_fma_f32 v207, v5, v46, v207
	v_fma_f32 v215, v4, v47, v215
	v_fma_f32 v208, v5, v48, v208
	v_fma_f32 v216, v4, v49, v216
	v_fma_f32 v209, v5, v50, v209
	v_fma_f32 v217, v4, v51, v217
	v_fma_f32 v210, v5, v52, v210
	v_fma_f32 v218, v4, v53, v218
	v_fma_f32 v211, v5, v54, v211
	v_fma_f32 v219, v4, v55, v219
	v_fma_f32 v204, v7, v42, v204
	v_fma_f32 v212, v6, v43, v212
	v_fma_f32 v205, v7, v44, v205
	v_fma_f32 v213, v6, v45, v213
	v_fma_f32 v206, v7, v46, v206
	v_fma_f32 v214, v6, v47, v214
	v_fma_f32 v207, v7, v48, v207
	v_fma_f32 v215, v6, v49, v215
	v_fma_f32 v208, v7, v50, v208
	v_fma_f32 v216, v6, v51, v216
	v_fma_f32 v209, v7, v52, v209
	v_fma_f32 v217, v6, v53, v217
	v_fma_f32 v210, v7, v54, v210
	v_fma_f32 v218, v6, v55, v218
	v_fma_f32 v211, v7, v56, v211
	v_fma_f32 v219, v6, v57, v219
	v_mul_f32_e32 v220, 0xbfb8aa3b, v204
	v_mul_f32_e32 v221, 0xbfb8aa3b, v205
	v_mul_f32_e32 v222, 0xbfb8aa3b, v206
	v_mul_f32_e32 v223, 0xbfb8aa3b, v207
	v_mul_f32_e32 v224, 0xbfb8aa3b, v208
	v_mul_f32_e32 v225, 0xbfb8aa3b, v209
	v_mul_f32_e32 v226, 0xbfb8aa3b, v210
	v_mul_f32_e32 v227, 0xbfb8aa3b, v211
	v_exp_f32_e32 v220, v220
	v_exp_f32_e32 v221, v221
	v_exp_f32_e32 v222, v222
	v_exp_f32_e32 v223, v223
	v_exp_f32_e32 v224, v224
	v_exp_f32_e32 v225, v225
	v_exp_f32_e32 v226, v226
	v_exp_f32_e32 v227, v227
	v_add_f32_e32 v220, 1.0, v220
	v_add_f32_e32 v221, 1.0, v221
	v_add_f32_e32 v222, 1.0, v222
	v_add_f32_e32 v223, 1.0, v223
	v_add_f32_e32 v224, 1.0, v224
	v_add_f32_e32 v225, 1.0, v225
	v_add_f32_e32 v226, 1.0, v226
	v_add_f32_e32 v227, 1.0, v227
	v_rcp_f32_e32 v220, v220
	v_rcp_f32_e32 v221, v221
	v_rcp_f32_e32 v222, v222
	v_rcp_f32_e32 v223, v223
	v_rcp_f32_e32 v224, v224
	v_rcp_f32_e32 v225, v225
	v_rcp_f32_e32 v226, v226
	v_rcp_f32_e32 v227, v227
	v_mul_f32_e32 v204, v204, v220
	v_mul_f32_e32 v205, v205, v221
	v_mul_f32_e32 v206, v206, v222
	v_mul_f32_e32 v207, v207, v223
	v_mul_f32_e32 v208, v208, v224
	v_mul_f32_e32 v209, v209, v225
	v_mul_f32_e32 v210, v210, v226
	v_mul_f32_e32 v211, v211, v227
	v_mul_f32_e32 v212, v212, v204
	v_mul_f32_e32 v213, v213, v205
	v_mul_f32_e32 v214, v214, v206
	v_mul_f32_e32 v215, v215, v207
	v_mul_f32_e32 v216, v216, v208
	v_mul_f32_e32 v217, v217, v209
	v_mul_f32_e32 v218, v218, v210
	v_mul_f32_e32 v219, v219, v211
	v_cvt_pk_bf16_f32 v212, v212, v213
	v_cvt_pk_bf16_f32 v214, v214, v215
	v_cvt_pk_bf16_f32 v216, v216, v217
	v_cvt_pk_bf16_f32 v218, v218, v219
	s_cmp_eq_u32 s61, 2
	s_cbranch_scc1 .Lcv5_mst1
	v_cmp_gt_i32_e32 vcc, 16, v34
	s_cmp_lg_u64 vcc, 0
	s_cbranch_scc1 .Lcv5_slowu1
	global_store_short v24, v212, s[42:43] offset:1024
	global_store_short_d16_hi v24, v212, s[42:43] offset:1152
	global_store_short v24, v214, s[42:43] offset:1280
	global_store_short_d16_hi v24, v214, s[42:43] offset:1408
	global_store_short v24, v216, s[42:43] offset:1536
	global_store_short_d16_hi v24, v216, s[42:43] offset:1664
	global_store_short v24, v218, s[42:43] offset:1792
	global_store_short_d16_hi v24, v218, s[42:43] offset:1920
	s_branch .Lcv5_next1
.Lcv5_slowu1:
	v_cmp_lt_i32_e32 vcc, 8, v34
	s_and_b64 exec, exec, vcc
	global_store_short v24, v212, s[42:43] offset:1024
	v_cmp_lt_i32_e32 vcc, 9, v34
	s_and_b64 exec, exec, vcc
	global_store_short_d16_hi v24, v212, s[42:43] offset:1152
	v_cmp_lt_i32_e32 vcc, 10, v34
	s_and_b64 exec, exec, vcc
	global_store_short v24, v214, s[42:43] offset:1280
	v_cmp_lt_i32_e32 vcc, 11, v34
	s_and_b64 exec, exec, vcc
	global_store_short_d16_hi v24, v214, s[42:43] offset:1408
	v_cmp_lt_i32_e32 vcc, 12, v34
	s_and_b64 exec, exec, vcc
	global_store_short v24, v216, s[42:43] offset:1536
	v_cmp_lt_i32_e32 vcc, 13, v34
	s_and_b64 exec, exec, vcc
	global_store_short_d16_hi v24, v216, s[42:43] offset:1664
	v_cmp_lt_i32_e32 vcc, 14, v34
	s_and_b64 exec, exec, vcc
	global_store_short v24, v218, s[42:43] offset:1792
	v_cmp_lt_i32_e32 vcc, 15, v34
	s_and_b64 exec, exec, vcc
	global_store_short_d16_hi v24, v218, s[42:43] offset:1920
	s_mov_b64 exec, -1
	s_branch .Lcv5_next1
.Lcv5_mst1:
	v_cmp_gt_i32_e32 vcc, 16, v34
	s_cmp_lg_u64 vcc, 0
	s_cbranch_scc1 .Lcv5_slowm1
	global_store_short v24, v212, s[42:43] offset:1024
	global_store_short_d16_hi v25, v212, s[42:43] offset:1152
	global_store_short v26, v214, s[42:43] offset:1280
	global_store_short_d16_hi v27, v214, s[42:43] offset:1408
	global_store_short v28, v216, s[42:43] offset:1536
	global_store_short_d16_hi v29, v216, s[42:43] offset:1664
	global_store_short v30, v218, s[42:43] offset:1792
	global_store_short_d16_hi v31, v218, s[42:43] offset:1920
	s_branch .Lcv5_next1

.Lcv5_next1:
	v_add_u32_e32 v17, 0x1020, v17
	v_add_u32_e32 v36, 1032, v17
	v_add_u32_e32 v37, 2064, v17
	v_add_u32_e32 v38, 3096, v17
	ds_read2_b32 v[188:189], v17 offset0:0 offset1:64
	ds_read2_b32 v[190:191], v17 offset0:129 offset1:193
	ds_read2_b32 v[192:193], v36 offset0:0 offset1:64
	ds_read2_b32 v[194:195], v36 offset0:129 offset1:193
	ds_read2_b32 v[196:197], v37 offset0:0 offset1:64
	ds_read2_b32 v[198:199], v37 offset0:129 offset1:193
	ds_read2_b32 v[200:201], v38 offset0:0 offset1:64
	ds_read2_b32 v[202:203], v38 offset0:129 offset1:193
	s_cmp_ge_i32 s64, 48
	s_cselect_b32 s62, 0xac000, 0
	s_cselect_b32 s61, 0, 1
	s_cbranch_scc1 .Lcv5_uni2
	s_cmp_lt_i32 s64, 41
	s_cbranch_scc1 .Lcv5_uni2
	s_mov_b32 s61, 2
	v_cmp_le_i32_e64 s[6:7], 48, v33
	v_cmp_le_i32_e64 s[8:9], 47, v33
	v_cmp_le_i32_e64 vcc, 46, v33
	v_cndmask_b32_e64 v24, v39, v35, s[6:7]
	v_cmp_le_i32_e64 s[6:7], 45, v33
	v_cndmask_b32_e64 v25, v39, v35, s[8:9]
	v_cmp_le_i32_e64 s[8:9], 44, v33
	v_cndmask_b32_e64 v26, v39, v35, vcc
	v_cmp_le_i32_e64 vcc, 43, v33
	v_cndmask_b32_e64 v27, v39, v35, s[6:7]
	v_cmp_le_i32_e64 s[6:7], 42, v33
	v_cndmask_b32_e64 v28, v39, v35, s[8:9]
	v_cmp_le_i32_e64 s[8:9], 41, v33
	v_cndmask_b32_e64 v29, v39, v35, vcc
	v_cndmask_b32_e64 v30, v39, v35, s[6:7]
	s_nop 0
	v_cndmask_b32_e64 v31, v39, v35, s[8:9]
	s_branch .Lcv5_adr2

.Lcv5_adr2:
	s_waitcnt lgkmcnt(0)
	v_fma_f32 v204, v3, v54, v9
	v_fma_f32 v212, v2, v55, v8
	v_fma_f32 v205, v3, v56, v9
	v_fma_f32 v213, v2, v57, v8
	v_fma_f32 v206, v3, v188, v9
	v_fma_f32 v214, v2, v189, v8
	v_fma_f32 v207, v3, v190, v9
	v_fma_f32 v215, v2, v191, v8
	v_fma_f32 v208, v3, v192, v9
	v_fma_f32 v216, v2, v193, v8
	v_fma_f32 v209, v3, v194, v9
	v_fma_f32 v217, v2, v195, v8
	v_fma_f32 v210, v3, v196, v9
	v_fma_f32 v218, v2, v197, v8
	v_fma_f32 v211, v3, v198, v9
	v_fma_f32 v219, v2, v199, v8
	v_fma_f32 v204, v5, v56, v204
	v_fma_f32 v212, v4, v57, v212
	v_fma_f32 v205, v5, v188, v205
	v_fma_f32 v213, v4, v189, v213
	v_fma_f32 v206, v5, v190, v206
	v_fma_f32 v214, v4, v191, v214
	v_fma_f32 v207, v5, v192, v207
	v_fma_f32 v215, v4, v193, v215
	v_fma_f32 v208, v5, v194, v208
	v_fma_f32 v216, v4, v195, v216
	v_fma_f32 v209, v5, v196, v209
	v_fma_f32 v217, v4, v197, v217
	v_fma_f32 v210, v5, v198, v210
	v_fma_f32 v218, v4, v199, v218
	v_fma_f32 v211, v5, v200, v211
	v_fma_f32 v219, v4, v201, v219
	v_fma_f32 v204, v7, v188, v204
	v_fma_f32 v212, v6, v189, v212
	v_fma_f32 v205, v7, v190, v205
	v_fma_f32 v213, v6, v191, v213
	v_fma_f32 v206, v7, v192, v206
	v_fma_f32 v214, v6, v193, v214
	v_fma_f32 v207, v7, v194, v207
	v_fma_f32 v215, v6, v195, v215
	v_fma_f32 v208, v7, v196, v208
	v_fma_f32 v216, v6, v197, v216
	v_fma_f32 v209, v7, v198, v209
	v_fma_f32 v217, v6, v199, v217
	v_fma_f32 v210, v7, v200, v210
	v_fma_f32 v218, v6, v201, v218
	v_fma_f32 v211, v7, v202, v211
	v_fma_f32 v219, v6, v203, v219
	v_mul_f32_e32 v220, 0xbfb8aa3b, v204
	v_mul_f32_e32 v221, 0xbfb8aa3b, v205
	v_mul_f32_e32 v222, 0xbfb8aa3b, v206
	v_mul_f32_e32 v223, 0xbfb8aa3b, v207
	v_mul_f32_e32 v224, 0xbfb8aa3b, v208
	v_mul_f32_e32 v225, 0xbfb8aa3b, v209
	v_mul_f32_e32 v226, 0xbfb8aa3b, v210
	v_mul_f32_e32 v227, 0xbfb8aa3b, v211
	v_exp_f32_e32 v220, v220
	v_exp_f32_e32 v221, v221
	v_exp_f32_e32 v222, v222
	v_exp_f32_e32 v223, v223
	v_exp_f32_e32 v224, v224
	v_exp_f32_e32 v225, v225
	v_exp_f32_e32 v226, v226
	v_exp_f32_e32 v227, v227
	v_add_f32_e32 v220, 1.0, v220
	v_add_f32_e32 v221, 1.0, v221
	v_add_f32_e32 v222, 1.0, v222
	v_add_f32_e32 v223, 1.0, v223
	v_add_f32_e32 v224, 1.0, v224
	v_add_f32_e32 v225, 1.0, v225
	v_add_f32_e32 v226, 1.0, v226
	v_add_f32_e32 v227, 1.0, v227
	v_rcp_f32_e32 v220, v220
	v_rcp_f32_e32 v221, v221
	v_rcp_f32_e32 v222, v222
	v_rcp_f32_e32 v223, v223
	v_rcp_f32_e32 v224, v224
	v_rcp_f32_e32 v225, v225
	v_rcp_f32_e32 v226, v226
	v_rcp_f32_e32 v227, v227
	v_mul_f32_e32 v204, v204, v220
	v_mul_f32_e32 v205, v205, v221
	v_mul_f32_e32 v206, v206, v222
	v_mul_f32_e32 v207, v207, v223
	v_mul_f32_e32 v208, v208, v224
	v_mul_f32_e32 v209, v209, v225
	v_mul_f32_e32 v210, v210, v226
	v_mul_f32_e32 v211, v211, v227
	v_mul_f32_e32 v212, v212, v204
	v_mul_f32_e32 v213, v213, v205
	v_mul_f32_e32 v214, v214, v206
	v_mul_f32_e32 v215, v215, v207
	v_mul_f32_e32 v216, v216, v208
	v_mul_f32_e32 v217, v217, v209
	v_mul_f32_e32 v218, v218, v210
	v_mul_f32_e32 v219, v219, v211
	v_cvt_pk_bf16_f32 v212, v212, v213
	v_cvt_pk_bf16_f32 v214, v214, v215
	v_cvt_pk_bf16_f32 v216, v216, v217
	v_cvt_pk_bf16_f32 v218, v218, v219
	s_cmp_eq_u32 s61, 2
	s_cbranch_scc1 .Lcv5_mst2
	v_cmp_gt_i32_e32 vcc, 24, v34
	s_cmp_lg_u64 vcc, 0
	s_cbranch_scc1 .Lcv5_slowu2
	global_store_short v24, v212, s[42:43] offset:2048
	global_store_short_d16_hi v24, v212, s[42:43] offset:2176
	global_store_short v24, v214, s[42:43] offset:2304
	global_store_short_d16_hi v24, v214, s[42:43] offset:2432
	global_store_short v24, v216, s[42:43] offset:2560
	global_store_short_d16_hi v24, v216, s[42:43] offset:2688
	global_store_short v24, v218, s[42:43] offset:2816
	global_store_short_d16_hi v24, v218, s[42:43] offset:2944
	s_branch .Lcv5_next2
.Lcv5_slowu2:
	v_cmp_lt_i32_e32 vcc, 16, v34
	s_and_b64 exec, exec, vcc
	global_store_short v24, v212, s[42:43] offset:2048
	v_cmp_lt_i32_e32 vcc, 17, v34
	s_and_b64 exec, exec, vcc
	global_store_short_d16_hi v24, v212, s[42:43] offset:2176
	v_cmp_lt_i32_e32 vcc, 18, v34
	s_and_b64 exec, exec, vcc
	global_store_short v24, v214, s[42:43] offset:2304
	v_cmp_lt_i32_e32 vcc, 19, v34
	s_and_b64 exec, exec, vcc
	global_store_short_d16_hi v24, v214, s[42:43] offset:2432
	v_cmp_lt_i32_e32 vcc, 20, v34
	s_and_b64 exec, exec, vcc
	global_store_short v24, v216, s[42:43] offset:2560
	v_cmp_lt_i32_e32 vcc, 21, v34
	s_and_b64 exec, exec, vcc
	global_store_short_d16_hi v24, v216, s[42:43] offset:2688
	v_cmp_lt_i32_e32 vcc, 22, v34
	s_and_b64 exec, exec, vcc
	global_store_short v24, v218, s[42:43] offset:2816
	v_cmp_lt_i32_e32 vcc, 23, v34
	s_and_b64 exec, exec, vcc
	global_store_short_d16_hi v24, v218, s[42:43] offset:2944
	s_mov_b64 exec, -1
	s_branch .Lcv5_next2
.Lcv5_mst2:
	v_cmp_gt_i32_e32 vcc, 24, v34
	s_cmp_lg_u64 vcc, 0
	s_cbranch_scc1 .Lcv5_slowm2
	global_store_short v24, v212, s[42:43] offset:2048
	global_store_short_d16_hi v25, v212, s[42:43] offset:2176
	global_store_short v26, v214, s[42:43] offset:2304
	global_store_short_d16_hi v27, v214, s[42:43] offset:2432
	global_store_short v28, v216, s[42:43] offset:2560
	global_store_short_d16_hi v29, v216, s[42:43] offset:2688
	global_store_short v30, v218, s[42:43] offset:2816
	global_store_short_d16_hi v31, v218, s[42:43] offset:2944
	s_branch .Lcv5_next2

.Lcv5_next2:
	v_add_u32_e32 v17, 0x1020, v17
	v_add_u32_e32 v36, 1032, v17
	v_add_u32_e32 v37, 2064, v17
	v_add_u32_e32 v38, 3096, v17
	ds_read2_b32 v[42:43], v17 offset0:0 offset1:64
	ds_read2_b32 v[44:45], v17 offset0:129 offset1:193
	ds_read2_b32 v[46:47], v36 offset0:0 offset1:64
	ds_read2_b32 v[48:49], v36 offset0:129 offset1:193
	ds_read2_b32 v[50:51], v37 offset0:0 offset1:64
	ds_read2_b32 v[52:53], v37 offset0:129 offset1:193
	ds_read2_b32 v[54:55], v38 offset0:0 offset1:64
	ds_read2_b32 v[56:57], v38 offset0:129 offset1:193
	s_cmp_ge_i32 s64, 40
	s_cselect_b32 s62, 0xac000, 0
	s_cselect_b32 s61, 0, 1
	s_cbranch_scc1 .Lcv5_uni3
	s_cmp_lt_i32 s64, 33
	s_cbranch_scc1 .Lcv5_uni3
	s_mov_b32 s61, 2
	v_cmp_le_i32_e64 s[6:7], 40, v33
	v_cmp_le_i32_e64 s[8:9], 39, v33
	v_cmp_le_i32_e64 vcc, 38, v33
	v_cndmask_b32_e64 v24, v39, v35, s[6:7]
	v_cmp_le_i32_e64 s[6:7], 37, v33
	v_cndmask_b32_e64 v25, v39, v35, s[8:9]
	v_cmp_le_i32_e64 s[8:9], 36, v33
	v_cndmask_b32_e64 v26, v39, v35, vcc
	v_cmp_le_i32_e64 vcc, 35, v33
	v_cndmask_b32_e64 v27, v39, v35, s[6:7]
	v_cmp_le_i32_e64 s[6:7], 34, v33
	v_cndmask_b32_e64 v28, v39, v35, s[8:9]
	v_cmp_le_i32_e64 s[8:9], 33, v33
	v_cndmask_b32_e64 v29, v39, v35, vcc
	v_cndmask_b32_e64 v30, v39, v35, s[6:7]
	s_nop 0
	v_cndmask_b32_e64 v31, v39, v35, s[8:9]
	s_branch .Lcv5_adr3

.Lcv5_adr3:
	s_waitcnt lgkmcnt(0)
	v_fma_f32 v204, v3, v200, v9
	v_fma_f32 v212, v2, v201, v8
	v_fma_f32 v205, v3, v202, v9
	v_fma_f32 v213, v2, v203, v8
	v_fma_f32 v206, v3, v42, v9
	v_fma_f32 v214, v2, v43, v8
	v_fma_f32 v207, v3, v44, v9
	v_fma_f32 v215, v2, v45, v8
	v_fma_f32 v208, v3, v46, v9
	v_fma_f32 v216, v2, v47, v8
	v_fma_f32 v209, v3, v48, v9
	v_fma_f32 v217, v2, v49, v8
	v_fma_f32 v210, v3, v50, v9
	v_fma_f32 v218, v2, v51, v8
	v_fma_f32 v211, v3, v52, v9
	v_fma_f32 v219, v2, v53, v8
	v_fma_f32 v204, v5, v202, v204
	v_fma_f32 v212, v4, v203, v212
	v_fma_f32 v205, v5, v42, v205
	v_fma_f32 v213, v4, v43, v213
	v_fma_f32 v206, v5, v44, v206
	v_fma_f32 v214, v4, v45, v214
	v_fma_f32 v207, v5, v46, v207
	v_fma_f32 v215, v4, v47, v215
	v_fma_f32 v208, v5, v48, v208
	v_fma_f32 v216, v4, v49, v216
	v_fma_f32 v209, v5, v50, v209
	v_fma_f32 v217, v4, v51, v217
	v_fma_f32 v210, v5, v52, v210
	v_fma_f32 v218, v4, v53, v218
	v_fma_f32 v211, v5, v54, v211
	v_fma_f32 v219, v4, v55, v219
	v_fma_f32 v204, v7, v42, v204
	v_fma_f32 v212, v6, v43, v212
	v_fma_f32 v205, v7, v44, v205
	v_fma_f32 v213, v6, v45, v213
	v_fma_f32 v206, v7, v46, v206
	v_fma_f32 v214, v6, v47, v214
	v_fma_f32 v207, v7, v48, v207
	v_fma_f32 v215, v6, v49, v215
	v_fma_f32 v208, v7, v50, v208
	v_fma_f32 v216, v6, v51, v216
	v_fma_f32 v209, v7, v52, v209
	v_fma_f32 v217, v6, v53, v217
	v_fma_f32 v210, v7, v54, v210
	v_fma_f32 v218, v6, v55, v218
	v_fma_f32 v211, v7, v56, v211
	v_fma_f32 v219, v6, v57, v219
	v_mul_f32_e32 v220, 0xbfb8aa3b, v204
	v_mul_f32_e32 v221, 0xbfb8aa3b, v205
	v_mul_f32_e32 v222, 0xbfb8aa3b, v206
	v_mul_f32_e32 v223, 0xbfb8aa3b, v207
	v_mul_f32_e32 v224, 0xbfb8aa3b, v208
	v_mul_f32_e32 v225, 0xbfb8aa3b, v209
	v_mul_f32_e32 v226, 0xbfb8aa3b, v210
	v_mul_f32_e32 v227, 0xbfb8aa3b, v211
	v_exp_f32_e32 v220, v220
	v_exp_f32_e32 v221, v221
	v_exp_f32_e32 v222, v222
	v_exp_f32_e32 v223, v223
	v_exp_f32_e32 v224, v224
	v_exp_f32_e32 v225, v225
	v_exp_f32_e32 v226, v226
	v_exp_f32_e32 v227, v227
	v_add_f32_e32 v220, 1.0, v220
	v_add_f32_e32 v221, 1.0, v221
	v_add_f32_e32 v222, 1.0, v222
	v_add_f32_e32 v223, 1.0, v223
	v_add_f32_e32 v224, 1.0, v224
	v_add_f32_e32 v225, 1.0, v225
	v_add_f32_e32 v226, 1.0, v226
	v_add_f32_e32 v227, 1.0, v227
	v_rcp_f32_e32 v220, v220
	v_rcp_f32_e32 v221, v221
	v_rcp_f32_e32 v222, v222
	v_rcp_f32_e32 v223, v223
	v_rcp_f32_e32 v224, v224
	v_rcp_f32_e32 v225, v225
	v_rcp_f32_e32 v226, v226
	v_rcp_f32_e32 v227, v227
	v_mul_f32_e32 v204, v204, v220
	v_mul_f32_e32 v205, v205, v221
	v_mul_f32_e32 v206, v206, v222
	v_mul_f32_e32 v207, v207, v223
	v_mul_f32_e32 v208, v208, v224
	v_mul_f32_e32 v209, v209, v225
	v_mul_f32_e32 v210, v210, v226
	v_mul_f32_e32 v211, v211, v227
	v_mul_f32_e32 v212, v212, v204
	v_mul_f32_e32 v213, v213, v205
	v_mul_f32_e32 v214, v214, v206
	v_mul_f32_e32 v215, v215, v207
	v_mul_f32_e32 v216, v216, v208
	v_mul_f32_e32 v217, v217, v209
	v_mul_f32_e32 v218, v218, v210
	v_mul_f32_e32 v219, v219, v211
	v_cvt_pk_bf16_f32 v212, v212, v213
	v_cvt_pk_bf16_f32 v214, v214, v215
	v_cvt_pk_bf16_f32 v216, v216, v217
	v_cvt_pk_bf16_f32 v218, v218, v219
	s_cmp_eq_u32 s61, 2
	s_cbranch_scc1 .Lcv5_mst3
	v_cmp_gt_i32_e32 vcc, 32, v34
	s_cmp_lg_u64 vcc, 0
	s_cbranch_scc1 .Lcv5_slowu3
	global_store_short v24, v212, s[42:43] offset:3072
	global_store_short_d16_hi v24, v212, s[42:43] offset:3200
	global_store_short v24, v214, s[42:43] offset:3328
	global_store_short_d16_hi v24, v214, s[42:43] offset:3456
	global_store_short v24, v216, s[42:43] offset:3584
	global_store_short_d16_hi v24, v216, s[42:43] offset:3712
	global_store_short v24, v218, s[42:43] offset:3840
	global_store_short_d16_hi v24, v218, s[42:43] offset:3968
	s_branch .Lcv5_next3
.Lcv5_slowu3:
	v_cmp_lt_i32_e32 vcc, 24, v34
	s_and_b64 exec, exec, vcc
	global_store_short v24, v212, s[42:43] offset:3072
	v_cmp_lt_i32_e32 vcc, 25, v34
	s_and_b64 exec, exec, vcc
	global_store_short_d16_hi v24, v212, s[42:43] offset:3200
	v_cmp_lt_i32_e32 vcc, 26, v34
	s_and_b64 exec, exec, vcc
	global_store_short v24, v214, s[42:43] offset:3328
	v_cmp_lt_i32_e32 vcc, 27, v34
	s_and_b64 exec, exec, vcc
	global_store_short_d16_hi v24, v214, s[42:43] offset:3456
	v_cmp_lt_i32_e32 vcc, 28, v34
	s_and_b64 exec, exec, vcc
	global_store_short v24, v216, s[42:43] offset:3584
	v_cmp_lt_i32_e32 vcc, 29, v34
	s_and_b64 exec, exec, vcc
	global_store_short_d16_hi v24, v216, s[42:43] offset:3712
	v_cmp_lt_i32_e32 vcc, 30, v34
	s_and_b64 exec, exec, vcc
	global_store_short v24, v218, s[42:43] offset:3840
	v_cmp_lt_i32_e32 vcc, 31, v34
	s_and_b64 exec, exec, vcc
	global_store_short_d16_hi v24, v218, s[42:43] offset:3968
	s_mov_b64 exec, -1
	s_branch .Lcv5_next3
.Lcv5_mst3:
	v_cmp_gt_i32_e32 vcc, 32, v34
	s_cmp_lg_u64 vcc, 0
	s_cbranch_scc1 .Lcv5_slowm3
	global_store_short v24, v212, s[42:43] offset:3072
	global_store_short_d16_hi v25, v212, s[42:43] offset:3200
	global_store_short v26, v214, s[42:43] offset:3328
	global_store_short_d16_hi v27, v214, s[42:43] offset:3456
	global_store_short v28, v216, s[42:43] offset:3584
	global_store_short_d16_hi v29, v216, s[42:43] offset:3712
	global_store_short v30, v218, s[42:43] offset:3840
	global_store_short_d16_hi v31, v218, s[42:43] offset:3968
	s_branch .Lcv5_next3

.LBB0_2400:
	s_or_b64 exec, exec, s[4:5]
	v_pk_mul_f32 v[2:3], v[2:3], v[66:67] op_sel_hi:[1,0]
	ds_write2_b32 v155, v2, v3 offset0:32 offset1:33
	v_pk_mul_f32 v[2:3], v[4:5], v[66:67] op_sel_hi:[1,0]
	ds_write2_b32 v155, v2, v3 offset0:34 offset1:35
	v_pk_mul_f32 v[2:3], v[6:7], v[66:67] op_sel_hi:[1,0]
	ds_write2_b32 v155, v2, v3 offset0:40 offset1:41
	v_pk_mul_f32 v[2:3], v[8:9], v[66:67] op_sel_hi:[1,0]
	ds_write2_b32 v155, v2, v3 offset0:42 offset1:43
	v_pk_mul_f32 v[2:3], v[10:11], v[66:67] op_sel_hi:[1,0]
	ds_write2_b32 v155, v2, v3 offset0:48 offset1:49
	v_pk_mul_f32 v[2:3], v[12:13], v[66:67] op_sel_hi:[1,0]
	ds_write2_b32 v155, v2, v3 offset0:50 offset1:51
	v_pk_mul_f32 v[2:3], v[14:15], v[66:67] op_sel_hi:[1,0]
	ds_write2_b32 v155, v2, v3 offset0:56 offset1:57
	v_pk_mul_f32 v[2:3], v[16:17], v[66:67] op_sel_hi:[1,0]
	v_pk_mul_f32 v[18:19], v[18:19], v[66:67] op_sel_hi:[1,0]
	ds_write2_b32 v155, v2, v3 offset0:58 offset1:59
	ds_write2_b32 v155, v18, v19 offset1:1
	v_pk_mul_f32 v[18:19], v[20:21], v[66:67] op_sel_hi:[1,0]
	ds_write2_b32 v155, v18, v19 offset0:2 offset1:3
	v_pk_mul_f32 v[18:19], v[22:23], v[66:67] op_sel_hi:[1,0]
	ds_write2_b32 v155, v18, v19 offset0:8 offset1:9
	v_pk_mul_f32 v[18:19], v[24:25], v[66:67] op_sel_hi:[1,0]
	ds_write2_b32 v155, v18, v19 offset0:10 offset1:11
	v_pk_mul_f32 v[18:19], v[26:27], v[66:67] op_sel_hi:[1,0]
	ds_write2_b32 v155, v18, v19 offset0:16 offset1:17
	v_pk_mul_f32 v[18:19], v[28:29], v[66:67] op_sel_hi:[1,0]
	ds_write2_b32 v155, v18, v19 offset0:18 offset1:19
	v_pk_mul_f32 v[18:19], v[30:31], v[66:67] op_sel_hi:[1,0]
	ds_write2_b32 v155, v18, v19 offset0:24 offset1:25
	v_pk_mul_f32 v[18:19], v[32:33], v[66:67] op_sel_hi:[1,0]
	ds_write2_b32 v155, v18, v19 offset0:26 offset1:27
	s_waitcnt lgkmcnt(0)
	s_barrier
	s_waitcnt vmcnt(0)
	v_mov_b32_e32 v3, v188
	v_mov_b32_e32 v5, v189
	v_mov_b32_e32 v7, v190
	v_mov_b32_e32 v9, v191
	s_mul_i32 s4, s37, 0x7e
	v_mov_b32_e32 v2, v192
	v_mov_b32_e32 v4, v193
	v_mov_b32_e32 v6, v194
	s_add_i32 s4, s25, s4
	v_mov_b32_e32 v8, v195
	ds_read_b32 v15, v159
	ds_read_b32 v10, v160
	ds_read_b32 v14, v161
	ds_read_b32 v11, v162
	s_mulk_i32 s38, 0x7c
	s_sub_i32 s10, s4, s38
	s_mov_b64 s[4:5], 0
	v_mov_b32_e32 v17, v158
	v_mov_b32_e32 v18, v156
	s_waitcnt vmcnt(0)
	s_add_i32 s63, s10, -2
	s_sub_i32 s64, s26, s36
	v_min_i32_e32 v40, s64, v157
	v_add_u32_e32 v40, s63, v40
	v_lshlrev_b32_e32 v41, 1, v114
	v_add_u32_e32 v32, s63, v18
	v_ashrrev_i32_e32 v220, 7, v32
	v_and_b32_e32 v24, 0x7f, v32
	v_mad_u32_u24 v220, v220, 44, s18
	v_subrev_u32_e32 v33, 64, v24
	v_lshlrev_b32_e32 v24, 7, v24
	v_sub_u32_e32 v34, v40, v32
	v_readfirstlane_b32 s64, v33
	v_lshl_or_b32 v24, v220, 14, v24
	v_add_u32_e32 v39, v24, v41
	v_add_u32_e32 v35, 0xac000, v39
	v_add_u32_e32 v36, 1032, v17
	v_add_u32_e32 v37, 2064, v17
	v_add_u32_e32 v38, 3096, v17
	ds_read2_b32 v[188:189], v17 offset0:0 offset1:64
	ds_read2_b32 v[190:191], v17 offset0:129 offset1:193
	ds_read2_b32 v[192:193], v36 offset0:0 offset1:64
	ds_read2_b32 v[194:195], v36 offset0:129 offset1:193
	ds_read2_b32 v[196:197], v37 offset0:0 offset1:64
	ds_read2_b32 v[198:199], v37 offset0:129 offset1:193
	ds_read2_b32 v[200:201], v38 offset0:0 offset1:64
	ds_read2_b32 v[202:203], v38 offset0:129 offset1:193
	s_cmp_ge_i32 s64, 64
	s_cselect_b32 s62, 0xac000, 0
	s_cselect_b32 s61, 0, 1
	s_cbranch_scc1 .Lcv12_uni0
	s_cmp_lt_i32 s64, 57
	s_cbranch_scc1 .Lcv12_uni0
	s_mov_b32 s61, 2
	v_cmp_le_i32_e64 s[6:7], 64, v33
	v_cmp_le_i32_e64 s[8:9], 63, v33
	v_cmp_le_i32_e64 vcc, 62, v33
	v_cndmask_b32_e64 v24, v39, v35, s[6:7]
	v_cmp_le_i32_e64 s[6:7], 61, v33
	v_cndmask_b32_e64 v25, v39, v35, s[8:9]
	v_cmp_le_i32_e64 s[8:9], 60, v33
	v_cndmask_b32_e64 v26, v39, v35, vcc
	v_cmp_le_i32_e64 vcc, 59, v33
	v_cndmask_b32_e64 v27, v39, v35, s[6:7]
	v_cmp_le_i32_e64 s[6:7], 58, v33
	v_cndmask_b32_e64 v28, v39, v35, s[8:9]
	v_cmp_le_i32_e64 s[8:9], 57, v33
	v_cndmask_b32_e64 v29, v39, v35, vcc
	v_cndmask_b32_e64 v30, v39, v35, s[6:7]
	s_nop 0
	v_cndmask_b32_e64 v31, v39, v35, s[8:9]
	s_branch .Lcv12_adr0
